# RG-LRU carry-in fold: the 16 device-scope aggregate loads per lane are issued back to back after the step barrier instead of one load per round trip (addresses formed before the barrier); on top of ve
# speedup vs baseline: 1.0063x; 1.0063x over previous
.LBB0_424:
	v_cndmask_b32_e64 v216, v212, 0, s[0:1]
	v_cndmask_b32_e64 v34, v209, 1.0, s[0:1]
	v_mul_f32_e32 v217, v34, v206
	v_fmac_f32_e32 v216, v205, v34
	v_cndmask_b32_e64 v214, v214, 0, s[0:1]
	v_cndmask_b32_e64 v34, v213, 1.0, s[0:1]
	v_mul_f32_e32 v215, v210, v34
	v_fmac_f32_e32 v214, v208, v34
	v_cndmask_b32_e64 v212, v225, 0, s[0:1]
	v_cndmask_b32_e64 v34, v222, 1.0, s[0:1]
	v_mul_f32_e32 v213, v220, v34
	v_fmac_f32_e32 v212, v211, v34
	v_cndmask_b32_e64 v210, v227, 0, s[0:1]
	v_cndmask_b32_e64 v34, v226, 1.0, s[0:1]
	v_mul_f32_e32 v211, v223, v34
	v_fmac_f32_e32 v210, v221, v34
	v_cndmask_b32_e64 v208, v230, 0, s[0:1]
	v_cndmask_b32_e64 v34, v229, 1.0, s[0:1]
	v_mul_f32_e32 v209, v228, v34
	v_fmac_f32_e32 v208, v224, v34
	v_cndmask_b32_e64 v206, v234, 0, s[0:1]
	v_cndmask_b32_e64 v34, v232, 1.0, s[0:1]
	v_cmp_gt_i32_e32 vcc, s24, v115
	v_cndmask_b32_e64 v218, v207, 0, s[0:1]
	v_cndmask_b32_e64 v219, v88, 1.0, s[0:1]
	v_mul_f32_e32 v207, v238, v34
	v_fmac_f32_e32 v206, v231, v34
	v_cndmask_b32_e64 v107, v236, 0, s[0:1]
	v_cndmask_b32_e64 v34, v235, 1.0, s[0:1]
	s_lshl_b64 s[14:15], s[22:23], 19
	v_cndmask_b32_e32 v88, 0, v126, vcc
	v_mul_f32_e32 v205, v237, v34
	v_fmac_f32_e32 v107, v233, v34
	v_lshl_add_u64 v[34:35], v[86:87], 0, s[14:15]
	v_lshlrev_b32_e32 v88, 3, v88
	v_lshl_add_u64 v[220:221], v[34:35], 0, v[88:89]
	v_cmp_gt_i32_e32 vcc, s24, v127
	s_nop 1
	v_cndmask_b32_e32 v88, 0, v128, vcc
	v_cmp_gt_i32_e32 vcc, s24, v129
	v_lshlrev_b32_e32 v88, 3, v88
	v_lshl_add_u64 v[222:223], v[34:35], 0, v[88:89]
	v_cndmask_b32_e32 v88, 0, v130, vcc
	v_cmp_gt_i32_e32 vcc, s24, v131
	v_lshlrev_b32_e32 v88, 3, v88
	v_lshl_add_u64 v[224:225], v[34:35], 0, v[88:89]
	v_cndmask_b32_e32 v88, 0, v132, vcc
	v_cmp_gt_i32_e32 vcc, s24, v133
	v_lshlrev_b32_e32 v88, 3, v88
	v_lshl_add_u64 v[226:227], v[34:35], 0, v[88:89]
	v_cndmask_b32_e32 v88, 0, v134, vcc
	v_cmp_gt_i32_e32 vcc, s24, v135
	v_lshlrev_b32_e32 v88, 3, v88
	v_lshl_add_u64 v[228:229], v[34:35], 0, v[88:89]
	v_cndmask_b32_e32 v88, 0, v136, vcc
	v_cmp_gt_i32_e32 vcc, s24, v137
	v_lshlrev_b32_e32 v88, 3, v88
	v_lshl_add_u64 v[230:231], v[34:35], 0, v[88:89]
	v_cndmask_b32_e32 v88, 0, v138, vcc
	v_cmp_gt_i32_e32 vcc, s24, v139
	v_lshlrev_b32_e32 v88, 3, v88
	v_lshl_add_u64 v[232:233], v[34:35], 0, v[88:89]
	v_cndmask_b32_e32 v88, 0, v140, vcc
	v_cmp_gt_i32_e32 vcc, s24, v141
	v_lshlrev_b32_e32 v88, 3, v88
	v_lshl_add_u64 v[234:235], v[34:35], 0, v[88:89]
	v_cndmask_b32_e32 v88, 0, v142, vcc
	v_cmp_gt_i32_e32 vcc, s24, v143
	v_lshlrev_b32_e32 v88, 3, v88
	v_lshl_add_u64 v[236:237], v[34:35], 0, v[88:89]
	v_cndmask_b32_e32 v88, 0, v144, vcc
	v_cmp_gt_i32_e32 vcc, s24, v145
	v_lshlrev_b32_e32 v88, 3, v88
	v_lshl_add_u64 v[238:239], v[34:35], 0, v[88:89]
	v_cndmask_b32_e32 v88, 0, v146, vcc
	v_cmp_gt_i32_e32 vcc, s24, v147
	v_lshlrev_b32_e32 v88, 3, v88
	v_lshl_add_u64 v[242:243], v[34:35], 0, v[88:89]
	v_cndmask_b32_e32 v88, 0, v148, vcc
	v_cmp_gt_i32_e32 vcc, s24, v149
	v_lshlrev_b32_e32 v88, 3, v88
	v_lshl_add_u64 v[244:245], v[34:35], 0, v[88:89]
	v_cndmask_b32_e32 v88, 0, v150, vcc
	v_cmp_gt_i32_e32 vcc, s24, v151
	v_lshlrev_b32_e32 v88, 3, v88
	v_lshl_add_u64 v[246:247], v[34:35], 0, v[88:89]
	v_cndmask_b32_e32 v88, 0, v152, vcc
	v_cmp_gt_i32_e32 vcc, s24, v153
	v_lshlrev_b32_e32 v88, 3, v88
	v_lshl_add_u64 v[248:249], v[34:35], 0, v[88:89]
	v_cndmask_b32_e32 v88, 0, v154, vcc
	v_cmp_gt_i32_e32 vcc, s24, v155
	v_lshlrev_b32_e32 v88, 3, v88
	v_lshl_add_u64 v[250:251], v[34:35], 0, v[88:89]
	v_cndmask_b32_e32 v88, 0, v156, vcc
	v_lshlrev_b32_e32 v88, 3, v88
	v_lshl_add_u64 v[34:35], v[34:35], 0, v[88:89]
	s_waitcnt lgkmcnt(0)
	s_barrier
	global_load_dwordx2 v[220:221], v[220:221], off sc1
	global_load_dwordx2 v[222:223], v[222:223], off sc1
	global_load_dwordx2 v[224:225], v[224:225], off sc1
	global_load_dwordx2 v[226:227], v[226:227], off sc1
	global_load_dwordx2 v[228:229], v[228:229], off sc1
	global_load_dwordx2 v[230:231], v[230:231], off sc1
	global_load_dwordx2 v[232:233], v[232:233], off sc1
	global_load_dwordx2 v[234:235], v[234:235], off sc1
	global_load_dwordx2 v[236:237], v[236:237], off sc1
	global_load_dwordx2 v[238:239], v[238:239], off sc1
	global_load_dwordx2 v[242:243], v[242:243], off sc1
	global_load_dwordx2 v[244:245], v[244:245], off sc1
	global_load_dwordx2 v[246:247], v[246:247], off sc1
	global_load_dwordx2 v[248:249], v[248:249], off sc1
	global_load_dwordx2 v[250:251], v[250:251], off sc1
	global_load_dwordx2 v[34:35], v[34:35], off sc1
	v_fmac_f32_e32 v218, 0, v219
	s_cmp_eq_u32 s24, 63
	s_cselect_b64 s[14:15], -1, 0
	v_cmp_gt_i32_e32 vcc, s24, v115
	s_waitcnt vmcnt(15)
	s_nop 1
	v_cndmask_b32_e32 v220, 1.0, v220, vcc
	v_cndmask_b32_e32 v221, 0, v221, vcc
	v_cmp_gt_i32_e32 vcc, s24, v127
	v_fmac_f32_e32 v221, 0, v220
	s_nop 0
	s_waitcnt vmcnt(14)
	v_cndmask_b32_e32 v222, 1.0, v222, vcc
	v_cndmask_b32_e32 v223, 0, v223, vcc
	v_cmp_gt_i32_e32 vcc, s24, v129
	v_fmac_f32_e32 v223, v222, v221
	v_mul_f32_e32 v222, v220, v222
	s_waitcnt vmcnt(13)
	v_cndmask_b32_e32 v224, 1.0, v224, vcc
	v_cndmask_b32_e32 v225, 0, v225, vcc
	v_cmp_gt_i32_e32 vcc, s24, v131
	v_fmac_f32_e32 v225, v224, v223
	v_mul_f32_e32 v224, v222, v224
	s_waitcnt vmcnt(12)
	v_cndmask_b32_e32 v226, 1.0, v226, vcc
	v_cndmask_b32_e32 v227, 0, v227, vcc
	v_cmp_gt_i32_e32 vcc, s24, v133
	v_fmac_f32_e32 v227, v226, v225
	v_mul_f32_e32 v226, v224, v226
	s_waitcnt vmcnt(11)
	v_cndmask_b32_e32 v228, 1.0, v228, vcc
	v_cndmask_b32_e32 v229, 0, v229, vcc
	v_cmp_gt_i32_e32 vcc, s24, v135
	v_fmac_f32_e32 v229, v228, v227
	v_mul_f32_e32 v228, v226, v228
	s_waitcnt vmcnt(10)
	v_cndmask_b32_e32 v230, 1.0, v230, vcc
	v_cndmask_b32_e32 v231, 0, v231, vcc
	v_cmp_gt_i32_e32 vcc, s24, v137
	v_fmac_f32_e32 v231, v230, v229
	v_mul_f32_e32 v230, v228, v230
	s_waitcnt vmcnt(9)
	v_cndmask_b32_e32 v232, 1.0, v232, vcc
	v_cndmask_b32_e32 v233, 0, v233, vcc
	v_cmp_gt_i32_e32 vcc, s24, v139
	v_fmac_f32_e32 v233, v232, v231
	v_mul_f32_e32 v232, v230, v232
	s_waitcnt vmcnt(8)
	v_cndmask_b32_e32 v234, 1.0, v234, vcc
	v_cndmask_b32_e32 v235, 0, v235, vcc
	v_cmp_gt_i32_e32 vcc, s24, v141
	v_fmac_f32_e32 v235, v234, v233
	v_mul_f32_e32 v234, v232, v234
	s_waitcnt vmcnt(7)
	v_cndmask_b32_e32 v236, 1.0, v236, vcc
	v_cndmask_b32_e32 v237, 0, v237, vcc
	v_cmp_gt_i32_e32 vcc, s24, v143
	v_fmac_f32_e32 v237, v236, v235
	v_mul_f32_e32 v236, v234, v236
	s_waitcnt vmcnt(6)
	v_cndmask_b32_e32 v238, 1.0, v238, vcc
	v_cndmask_b32_e32 v239, 0, v239, vcc
	v_cmp_gt_i32_e32 vcc, s24, v145
	v_fmac_f32_e32 v239, v238, v237
	v_mul_f32_e32 v238, v236, v238
	s_waitcnt vmcnt(5)
	v_cndmask_b32_e32 v242, 1.0, v242, vcc
	v_cndmask_b32_e32 v243, 0, v243, vcc
	v_cmp_gt_i32_e32 vcc, s24, v147
	v_fmac_f32_e32 v243, v242, v239
	v_mul_f32_e32 v242, v238, v242
	s_waitcnt vmcnt(4)
	v_cndmask_b32_e32 v244, 1.0, v244, vcc
	v_cndmask_b32_e32 v245, 0, v245, vcc
	v_cmp_gt_i32_e32 vcc, s24, v149
	v_fmac_f32_e32 v245, v244, v243
	v_mul_f32_e32 v244, v242, v244
	s_waitcnt vmcnt(3)
	v_cndmask_b32_e32 v246, 1.0, v246, vcc
	v_cndmask_b32_e32 v247, 0, v247, vcc
	v_cmp_gt_i32_e32 vcc, s24, v151
	v_fmac_f32_e32 v247, v246, v245
	v_mul_f32_e32 v246, v244, v246
	s_waitcnt vmcnt(2)
	v_cndmask_b32_e32 v248, 1.0, v248, vcc
	v_cndmask_b32_e32 v249, 0, v249, vcc
	v_cmp_gt_i32_e32 vcc, s24, v153
	v_fmac_f32_e32 v249, v248, v247
	v_mul_f32_e32 v248, v246, v248
	s_waitcnt vmcnt(1)
	v_cndmask_b32_e32 v250, 1.0, v250, vcc
	v_cndmask_b32_e32 v251, 0, v251, vcc
	v_cmp_gt_i32_e32 vcc, s24, v155
	v_fmac_f32_e32 v251, v250, v249
	v_mul_f32_e32 v250, v248, v250
	s_waitcnt vmcnt(0)
	v_cndmask_b32_e32 v34, 1.0, v34, vcc
	v_cndmask_b32_e32 v35, 0, v35, vcc
	v_fmac_f32_e32 v35, v34, v251
	v_mul_f32_e32 v34, v250, v34
	s_and_b64 s[24:25], s[6:7], s[14:15]
	ds_bpermute_b32 v88, v122, v34
	ds_bpermute_b32 v220, v122, v35
	ds_bpermute_b32 v221, v157, v35
	s_waitcnt lgkmcnt(1)
	v_fmac_f32_e32 v220, 0, v88
	ds_bpermute_b32 v88, v157, v34
	s_waitcnt lgkmcnt(0)
	v_fmac_f32_e32 v221, v220, v88
	ds_bpermute_b32 v88, v158, v34
	ds_bpermute_b32 v220, v158, v35
	ds_bpermute_b32 v34, v123, v34
	ds_bpermute_b32 v35, v123, v35
	s_waitcnt lgkmcnt(2)
	v_fmac_f32_e32 v220, v221, v88
	s_waitcnt lgkmcnt(0)
	v_fmac_f32_e32 v35, v220, v34
	v_fmac_f32_e32 v218, v219, v35
	v_fmac_f32_e32 v216, v217, v35
	v_fmac_f32_e32 v214, v215, v35
	v_fmac_f32_e32 v212, v213, v35
	v_fmac_f32_e32 v210, v211, v35
	v_fmac_f32_e32 v208, v209, v35
	v_fmac_f32_e32 v206, v207, v35
	v_fmac_f32_e32 v107, v205, v35
	v_fmac_f32_e32 v174, v172, v218
	v_fmac_f32_e32 v184, v182, v216
	v_fmac_f32_e32 v79, v78, v214
	v_fmac_f32_e32 v71, v70, v212
	v_fmac_f32_e32 v63, v62, v210
	v_fmac_f32_e32 v52, v54, v208
	v_fmac_f32_e32 v47, v46, v206
	v_fmac_f32_e32 v36, v201, v107
	v_fmac_f32_e32 v179, v173, v174
	v_fmac_f32_e32 v189, v183, v184
	v_fmac_f32_e32 v191, v75, v79
	v_fmac_f32_e32 v193, v67, v71
	v_fmac_f32_e32 v195, v59, v63
	v_fmac_f32_e32 v197, v51, v52
	v_fmac_f32_e32 v199, v43, v47
	v_fmac_f32_e32 v204, v39, v36
	v_fmac_f32_e32 v178, v176, v179
	v_fmac_f32_e32 v188, v186, v189
	v_fmac_f32_e32 v81, v80, v191
	v_fmac_f32_e32 v73, v72, v193
	v_fmac_f32_e32 v65, v64, v195
	v_fmac_f32_e32 v57, v56, v197
	v_fmac_f32_e32 v49, v48, v199
	v_fmac_f32_e32 v203, v202, v204
	v_fmac_f32_e32 v180, v177, v178
	v_fmac_f32_e32 v190, v187, v188
	v_fmac_f32_e32 v192, v77, v81
	v_fmac_f32_e32 v194, v69, v73
	v_fmac_f32_e32 v196, v61, v65
	v_fmac_f32_e32 v198, v53, v57
	v_fmac_f32_e32 v200, v45, v49
	v_fmac_f32_e32 v37, v41, v203
	ds_write2_b32 v125, v174, v179 offset1:132
	ds_write2_b32 v175, v178, v180 offset0:8 offset1:140
	ds_write2_b32 v181, v184, v189 offset0:64 offset1:196
	ds_write2_b32 v185, v188, v190 offset0:72 offset1:204
	ds_write2_b32 v74, v79, v191 offset1:132
	ds_write2_b32 v76, v81, v192 offset0:8 offset1:140
	ds_write2_b32 v66, v71, v193 offset0:64 offset1:196
	ds_write2_b32 v68, v73, v194 offset0:72 offset1:204
	ds_write2_b32 v58, v63, v195 offset1:132
	ds_write2_b32 v60, v65, v196 offset0:8 offset1:140
	ds_write2_b32 v50, v52, v197 offset0:64 offset1:196
	ds_write2_b32 v55, v57, v198 offset0:72 offset1:204
	ds_write2_b32 v42, v47, v199 offset1:132
	ds_write2_b32 v44, v49, v200 offset0:8 offset1:140
	ds_write2_b32 v38, v36, v204 offset0:64 offset1:196
	ds_write2_b32 v40, v203, v37 offset0:72 offset1:204
	s_and_saveexec_b64 s[14:15], s[24:25]
	s_cbranch_execz .LBB0_406
	s_lshl_b64 s[24:25], s[22:23], 12
	s_add_u32 s24, s88, s24
	s_addc_u32 s25, s89, s25
	v_lshl_add_u64 v[34:35], v[84:85], 2, s[24:25]
	v_add_co_u32_e32 v34, vcc, 0x8300000, v34
	s_nop 1
	v_addc_co_u32_e32 v35, vcc, 0, v35, vcc
	global_store_dword v[34:35], v37, off
	s_branch .LBB0_406
